# attention V tiles staged row-major (one 16B LDS store per thread), PV fragments via ds_read_b64_tr_b16
# speedup vs baseline: 1.0066x; 1.0066x over previous
; #define LAS __attribute__((address_space(3)))
; #define LDS_BARRIER() asm volatile("s_waitcnt lgkmcnt(0)\n\ts_barrier" ::: "memory")
; #define AT_LOAD(K_, V_, kt) do { const bf16_t* s_ = kvsrc + (size_t)(kt) * 64 * NQKV; K_ = *(const bf16x8*)s_; V_ = *(const bf16x8*)(s_ + 1024); } while (0)
; #define AT_STORE(K_, V_, buf) do { *(LAS bf16x8*)(lds + AT_KOFF + (buf) * 9216 + srow * 144 + sch * 16) = K_; \
;         _Pragma("unroll") for (int j_ = 0; j_ < 8; ++j_) *(LAS short*)(lds + AT_VOFF + (buf) * 9216 + (8 * sch + j_) * 144 + vp * 2) = V_[j_]; } while (0)
; __device__ __forceinline__ void attn_prompt_unit(const Params& P, LAS unsigned char* lds, int li, int b, int h, int g4, const int tid) {
;     ...
;     const size_t qrow = (size_t)b * SEQ + 256 * g4 + 32 * wid + r32;
;     bf16x8 qr[4];
; #pragma unroll
;     for (int d0 = 0; d0 < 4; ++d0) qr[d0] = *(const bf16x8*)(QKV + qrow * NQKV + h * 64 + d0 * 16 + hi * 8);
;     const int kt_lo = max(0, 4 * g4 - 8), kt_hi = 4 * g4 + 3;
;     const int srow = tid & 63, sch = tid >> 6;
;     const bf16_t* kvsrc = QKV + ((size_t)b * SEQ + srow) * NQKV + 1024 + h * 64 + 8 * sch;
;     const int vp = vpos(srow);
;     bf16x8 kA, vA, kB, vB;
;     ...
;     AT_LOAD(kA, vA, kt_lo); AT_LOAD(kB, vB, kt_lo + 1);
;     AT_STORE(kA, vA, 0);
;     LDS_BARRIER();
;     float m = -1e30f, l = 0.f; f32x16 o[2];
; #pragma unroll
;     for (int r = 0; r < 16; ++r) { o[0][r] = 0.f; o[1][r] = 0.f; }
;     const LAS f32x4* btl = (const LAS f32x4*)(lds + AT_BIAS) + (wid & 1) * 512 + lane;
.LBB0_69:
	s_ashr_i32 s0, s2, 8
	s_and_b32 s15, s2, 15
	v_readfirstlane_b32 s18, v110
	s_ashr_i32 s1, s0, 31
	s_lshl_b64 s[22:23], s[0:1], 12
	s_lshl_b32 s26, s18, 5
	v_lshl_or_b32 v0, s15, 8, v109
	s_ashr_i32 s27, s26, 31
	v_or_b32_e32 v0, s22, v0
	v_mov_b32_e32 v1, s23
	v_lshl_add_u64 v[104:105], v[0:1], 0, s[26:27]
	v_mov_b64_e32 v[0:1], s[64:65]
	s_lshl_b32 s1, s2, 2
	v_or_b32_e32 v4, s22, v164
	v_mad_u64_u32 v[2:3], s[26:27], v104, s66, v[0:1]
	s_and_b32 s1, s1, 0x3c0
	v_mad_u64_u32 v[0:1], s[26:27], v4, s66, v[0:1]
	s_lshl_b32 s36, s1, 1
	v_mad_i32_i24 v1, s23, v198, v1
	s_lshl_b32 s15, s15, 2
	v_lshl_add_u64 v[0:1], v[0:1], 0, s[36:37]
	v_sub_u32_e64 v16, s15, 8 clamp
	v_lshl_add_u64 v[0:1], v[96:97], 1, v[0:1]
	s_mov_b32 s1, 0x60000
	v_mad_i32_i24 v3, v105, s66, v3
	v_mad_u64_u32 v[4:5], s[22:23], v16, s1, v[0:1]
	s_mov_b64 s[26:27], 0x800
	v_lshl_add_u64 v[2:3], v[2:3], 0, s[36:37]
	v_lshl_add_u64 v[6:7], v[4:5], 0, s[26:27]
	global_load_dwordx4 v[76:79], v[4:5], off offset:2048
	global_load_dwordx4 v[84:87], v[6:7], off offset:2048
	v_mov_b32_e32 v101, v161
	v_lshl_add_u64 v[2:3], v[2:3], 0, v[100:101]
	s_max_u32 s1, s15, 8
	global_load_dwordx4 v[64:67], v[2:3], off
	global_load_dwordx4 v[68:71], v[2:3], off offset:32
	global_load_dwordx4 v[72:75], v[2:3], off offset:64
	global_load_dwordx4 v[80:83], v[2:3], off offset:96
	s_add_i32 s1, s1, -7
	v_mad_u64_u32 v[0:1], s[22:23], s1, v199, v[0:1]
	v_lshl_add_u64 v[2:3], v[0:1], 0, s[26:27]
	global_load_dwordx4 v[88:91], v[0:1], off offset:2048
	global_load_dwordx4 v[92:95], v[2:3], off offset:2048
	s_or_b32 s17, s15, 3
	v_mov_b32_e32 v15, 0
	v_cmp_lt_u32_e32 vcc, s17, v16
	v_mov_b32_e32 v14, v15
	v_mov_b32_e32 v13, v15
	v_mov_b32_e32 v12, v15
	s_waitcnt vmcnt(8)
	v_mov_b32_e32 v11, v15
	v_mov_b32_e32 v10, v15
	v_mov_b32_e32 v9, v15
	v_mov_b32_e32 v8, v15
	v_mov_b32_e32 v7, v15
	v_mov_b32_e32 v6, v15
	v_mov_b32_e32 v5, v15
	v_mov_b32_e32 v4, v15
	v_mov_b32_e32 v3, v15
	v_mov_b32_e32 v2, v15
	v_mov_b32_e32 v1, v15
	v_mov_b32_e32 v0, v15
	v_mov_b32_e32 v31, v15
	v_mov_b32_e32 v30, v15
	v_mov_b32_e32 v29, v15
	v_mov_b32_e32 v28, v15
	v_mov_b32_e32 v27, v15
	v_mov_b32_e32 v26, v15
	v_mov_b32_e32 v25, v15
	v_mov_b32_e32 v24, v15
	v_mov_b32_e32 v23, v15
	v_mov_b32_e32 v22, v15
	v_mov_b32_e32 v21, v15
	v_mov_b32_e32 v20, v15
	v_mov_b32_e32 v19, v15
	v_readfirstlane_b32 s28, v16
	s_and_b64 vcc, exec, vcc
	v_mov_b32_e32 v18, v15
	v_mov_b32_e32 v17, v15
	v_mov_b32_e32 v16, v15
	v_mov_b32_e32 v101, v15
	s_waitcnt vmcnt(7)
	ds_write_b128 v114, v[76:79]
	s_waitcnt vmcnt(6)
	ds_write_b128 v114, v[84:87] offset:18432
	s_waitcnt lgkmcnt(0)
	s_barrier
	s_cbranch_vccnz .LBB0_68
	s_ashr_i32 s26, s18, 1
	s_lshl_b32 s18, s18, 13
	s_max_u32 s1, s13, 8
	s_lshl_b32 s19, s12, 1
	s_and_b32 s18, s18, 0x2000
	s_sub_i32 s22, 0, s1
	s_and_b32 s19, s19, 0x780
	s_mul_i32 s1, s1, 0x60000
	s_add_i32 s23, s26, s15
	v_add_u32_e32 v103, s18, v111
	s_mul_hi_i32 s18, s0, 0x1800000
	s_mul_i32 s0, s0, 0x1800000
	s_add_i32 s1, s1, 0xffd00000
	s_add_i32 s25, s23, -8
	s_add_i32 s26, s26, s14
	s_or_b32 s0, s0, s19
	s_add_u32 s0, s0, s1
	s_addc_u32 s1, s18, 0
	v_mov_b32_e32 v101, 0
	v_lshl_add_u64 v[106:107], v[98:99], 0, s[0:1]
	v_mov_b32_e32 v117, 0xf149f2ca
	v_mov_b32_e32 v16, 0
	v_mov_b32_e32 v17, v101
	v_mov_b32_e32 v18, v101
	v_mov_b32_e32 v19, v101
	v_mov_b32_e32 v20, v101
	v_mov_b32_e32 v21, v101
	v_mov_b32_e32 v22, v101
	v_mov_b32_e32 v23, v101
	v_mov_b32_e32 v24, v101
	v_mov_b32_e32 v25, v101
	v_mov_b32_e32 v26, v101
	v_mov_b32_e32 v27, v101
	v_mov_b32_e32 v28, v101
	v_mov_b32_e32 v29, v101
	v_mov_b32_e32 v30, v101
	v_mov_b32_e32 v31, v101
	v_mov_b32_e32 v0, v101
	v_mov_b32_e32 v1, v101
	v_mov_b32_e32 v2, v101
	v_mov_b32_e32 v3, v101
	v_mov_b32_e32 v4, v101
	v_mov_b32_e32 v5, v101
	v_mov_b32_e32 v6, v101
	v_mov_b32_e32 v7, v101
	v_mov_b32_e32 v8, v101
	v_mov_b32_e32 v9, v101
	v_mov_b32_e32 v10, v101
	v_mov_b32_e32 v11, v101
	v_mov_b32_e32 v12, v101
	v_mov_b32_e32 v13, v101
	v_mov_b32_e32 v14, v101
	v_mov_b32_e32 v15, v101

; #define LAS __attribute__((address_space(3)))
; __device__ __forceinline__ void attn_tile(const LAS unsigned char* Kb, const LAS unsigned char* Vb, const LAS f32x4* bp, const bf16x8 (&qr)[4], f32x16 (&o)[2], float& m, float& l, int r32, int hi) {
;     const float C2 = 0.125f * LOG2E;
;     f32x16 p0, p1;
; #pragma unroll
;     for (int j = 0; j < 4; ++j) { const f32x4 t0 = bp[j * 64], t1 = bp[(4 + j) * 64];
;         p0[4 * j] = t0[0]; p0[4 * j + 1] = t0[1]; p0[4 * j + 2] = t0[2]; p0[4 * j + 3] = t0[3]; p1[4 * j] = t1[0]; p1[4 * j + 1] = t1[1]; p1[4 * j + 2] = t1[2]; p1[4 * j + 3] = t1[3]; }
; #pragma unroll
;     for (int d0 = 0; d0 < 4; ++d0) {
;         const bf16x8 a0 = *(const LAS bf16x8*)(Kb + r32 * 144 + d0 * 32 + hi * 16);
;         const bf16x8 a1 = *(const LAS bf16x8*)(Kb + (32 + r32) * 144 + d0 * 32 + hi * 16);
;         p0 = __builtin_amdgcn_mfma_f32_32x32x16_bf16(a0, qr[d0], p0, 0, 0, 0);
;         p1 = __builtin_amdgcn_mfma_f32_32x32x16_bf16(a1, qr[d0], p1, 0, 0, 0);
;     }
;     float mx = fmaxf(p0[0], p1[0]);
; #pragma unroll
;     for (int r = 1; r < 16; ++r) mx = fmaxf(mx, fmaxf(p0[r], p1[r]));
;     mx = fmaxf(mx, __shfl_xor(mx, 32)) * C2;
;     if (__any(mx > m + 8.0f)) {
;         const float mn = fmaxf(m, mx), scl = __builtin_amdgcn_exp2f(m - mn); m = mn; l *= scl;
; #pragma unroll
;         for (int r = 0; r < 16; ++r) { o[0][r] *= scl; o[1][r] *= scl; }
;     }
;     float ls = 0.f; const float nm = -m;
; #pragma unroll
;     for (int r = 0; r < 16; ++r) { p0[r] = __builtin_amdgcn_exp2f(p0[r] * C2 + nm); p1[r] = __builtin_amdgcn_exp2f(p1[r] * C2 + nm); ls += p0[r] + p1[r]; }
;     l += ls;
;     u32x4 pw[4];
; #pragma unroll
;     for (int s = 0; s < 2; ++s) {
;         pw[s] = (u32x4){pk2(p0[8 * s], p0[8 * s + 1]), pk2(p0[8 * s + 2], p0[8 * s + 3]), pk2(p0[8 * s + 4], p0[8 * s + 5]), pk2(p0[8 * s + 6], p0[8 * s + 7])};
;         pw[2 + s] = (u32x4){pk2(p1[8 * s], p1[8 * s + 1]), pk2(p1[8 * s + 2], p1[8 * s + 3]), pk2(p1[8 * s + 4], p1[8 * s + 5]), pk2(p1[8 * s + 6], p1[8 * s + 7])};
;     }
; #pragma unroll
;     for (int dh = 0; dh < 2; ++dh)
; #pragma unroll
;         for (int ks = 0; ks < 4; ++ks) {
;             const bf16x8 vf = *(const LAS bf16x8*)(Vb + (32 * dh + r32) * 144 + (16 * ks + 8 * hi) * 2);
.LBB0_73:
	s_cmp_lt_i32 s28, s25
	s_cselect_b64 s[30:31], -1, 0
	s_cmp_gt_i32 s28, s23
	s_cselect_b64 s[34:35], -1, 0
	s_or_b64 s[30:31], s[30:31], s[34:35]
	s_and_b64 vcc, exec, s[30:31]
	s_cbranch_vccnz .LBB0_77
	s_add_i32 s29, s22, s26
	s_add_i32 s29, s29, 1
	s_min_i32 s29, s29, 3
	v_lshl_add_u32 v158, s29, 14, v103
	ds_read_b128 v[48:51], v158 offset:36864
	ds_read_b128 v[52:55], v158 offset:37888
	ds_read_b128 v[56:59], v158 offset:38912
	ds_read_b128 v[60:63], v158 offset:39936
	ds_read_b128 v[138:141], v116 offset:0
	ds_read_b128 v[142:145], v116 offset:4608
	ds_read_b128 v[32:35], v158 offset:40960
	ds_read_b128 v[36:39], v158 offset:41984
	ds_read_b128 v[40:43], v158 offset:43008
	ds_read_b128 v[44:47], v158 offset:44032
	ds_read_b128 v[146:149], v116 offset:32
	ds_read_b128 v[150:153], v116 offset:4640
	ds_read_b128 v[154:157], v116 offset:64
	ds_read_b128 v[118:121], v116 offset:4672
	ds_read_b128 v[122:125], v116 offset:96
	v_lshrrev_b32_e32 v133, 5, v200
	v_bfe_u32 v159, v200, 2, 2
	v_lshl_add_u32 v133, v133, 2, v159
	v_mul_u32_u24_e32 v133, 0x90, v133
	v_bfe_u32 v159, v200, 4, 1
	v_lshl_add_u32 v133, v159, 5, v133
	v_and_b32_e32 v159, 3, v200
	v_lshl_add_u32 v133, v159, 3, v133
	v_xor_b32_e32 v132, 32, v200
	s_waitcnt vmcnt(2) lgkmcnt(10)
	v_mfma_f32_32x32x16_bf16 v[48:63], v[138:141], v[64:67], v[48:63]
	ds_read_b128 v[126:129], v116 offset:4704
	s_waitcnt lgkmcnt(6)
	v_mfma_f32_32x32x16_bf16 v[32:47], v[142:145], v[64:67], v[32:47]
	v_lshlrev_b32_e32 v132, 2, v132
	s_waitcnt lgkmcnt(5)
	v_mfma_f32_32x32x16_bf16 v[48:63], v[146:149], v[68:71], v[48:63]
	s_waitcnt lgkmcnt(4)
	v_mfma_f32_32x32x16_bf16 v[32:47], v[150:153], v[68:71], v[32:47]
	s_waitcnt lgkmcnt(3)
	v_mfma_f32_32x32x16_bf16 v[48:63], v[154:157], v[72:75], v[48:63]
	s_waitcnt lgkmcnt(2)
	v_mfma_f32_32x32x16_bf16 v[32:47], v[118:121], v[72:75], v[32:47]
	s_waitcnt lgkmcnt(1)
	v_mfma_f32_32x32x16_bf16 v[48:63], v[122:125], v[80:83], v[48:63]
	s_waitcnt lgkmcnt(0)
	v_mfma_f32_32x32x16_bf16 v[32:47], v[126:129], v[80:83], v[32:47]
	ds_read_b64_tr_b16 v[138:139], v133 offset:18432
	ds_read_b64_tr_b16 v[140:141], v133 offset:19584
	ds_read_b64_tr_b16 v[142:143], v133 offset:20736
	ds_read_b64_tr_b16 v[144:145], v133 offset:21888
	ds_read_b64_tr_b16 v[146:147], v133 offset:23040
	ds_read_b64_tr_b16 v[148:149], v133 offset:24192
	ds_read_b64_tr_b16 v[150:151], v133 offset:25344
	ds_read_b64_tr_b16 v[152:153], v133 offset:26496
	v_add_f32_e32 v159, 0x41000000, v117
	s_nop 1
	v_max3_f32 v130, v48, v49, v50
	v_max3_f32 v130, v130, v51, v52
	v_max3_f32 v130, v130, v53, v54
	v_max3_f32 v131, v32, v33, v34
	v_max3_f32 v130, v130, v55, v56
	v_max3_f32 v131, v131, v35, v36
	v_max3_f32 v130, v130, v57, v58
	v_max3_f32 v131, v131, v37, v38
	v_max3_f32 v130, v130, v59, v60
	v_max3_f32 v131, v131, v39, v40
	v_max3_f32 v130, v130, v61, v62
	v_max3_f32 v131, v131, v41, v42
	v_max_f32_e32 v130, v130, v63
	v_max3_f32 v131, v131, v43, v44
	v_max3_f32 v131, v131, v45, v46
	v_max_f32_e32 v131, v131, v47
	v_max_f32_e32 v130, v130, v131
	ds_bpermute_b32 v131, v132, v130
	s_waitcnt lgkmcnt(0)
	v_max_f32_e32 v130, v130, v131
	v_mul_f32_e32 v130, 0x3e38aa3b, v130
	v_cmp_gt_f32_e32 vcc, v130, v159
	ds_read_b64_tr_b16 v[154:155], v133 offset:18496
	ds_read_b64_tr_b16 v[156:157], v133 offset:19648
	ds_read_b64_tr_b16 v[118:119], v133 offset:20800
	ds_read_b64_tr_b16 v[120:121], v133 offset:21952
	ds_read_b64_tr_b16 v[122:123], v133 offset:23104
	ds_read_b64_tr_b16 v[124:125], v133 offset:24256
	ds_read_b64_tr_b16 v[126:127], v133 offset:25408
	ds_read_b64_tr_b16 v[128:129], v133 offset:26560
	s_cbranch_vccz .Latt_keep_a
	v_max_f32_e32 v131, v117, v130
	v_sub_f32_e32 v117, v117, v131
	v_exp_f32_e32 v130, v117
	v_mov_b32_e32 v117, v131
	v_mul_f32_e32 v101, v101, v130
	v_pk_mul_f32 v[0:1], v[0:1], v[130:131] op_sel_hi:[1,0]
	v_pk_mul_f32 v[2:3], v[2:3], v[130:131] op_sel_hi:[1,0]
	v_pk_mul_f32 v[4:5], v[4:5], v[130:131] op_sel_hi:[1,0]
	v_pk_mul_f32 v[6:7], v[6:7], v[130:131] op_sel_hi:[1,0]
	v_pk_mul_f32 v[8:9], v[8:9], v[130:131] op_sel_hi:[1,0]
	v_pk_mul_f32 v[10:11], v[10:11], v[130:131] op_sel_hi:[1,0]
	v_pk_mul_f32 v[12:13], v[12:13], v[130:131] op_sel_hi:[1,0]
	v_pk_mul_f32 v[14:15], v[14:15], v[130:131] op_sel_hi:[1,0]
	v_pk_mul_f32 v[16:17], v[16:17], v[130:131] op_sel_hi:[1,0]
	v_pk_mul_f32 v[18:19], v[18:19], v[130:131] op_sel_hi:[1,0]
	v_pk_mul_f32 v[20:21], v[20:21], v[130:131] op_sel_hi:[1,0]
	v_pk_mul_f32 v[22:23], v[22:23], v[130:131] op_sel_hi:[1,0]
	v_pk_mul_f32 v[24:25], v[24:25], v[130:131] op_sel_hi:[1,0]
	v_pk_mul_f32 v[26:27], v[26:27], v[130:131] op_sel_hi:[1,0]
	v_pk_mul_f32 v[28:29], v[28:29], v[130:131] op_sel_hi:[1,0]
	v_pk_mul_f32 v[30:31], v[30:31], v[130:131] op_sel_hi:[1,0]
; #define LAS __attribute__((address_space(3)))
; __device__ __forceinline__ unsigned pk2(float lo, float hi) { const f32x2 v = {lo, hi}; return __builtin_bit_cast(unsigned, __builtin_convertvector(v, hwbf16x2)); }
; #define LDS_BARRIER() asm volatile("s_waitcnt lgkmcnt(0)\n\ts_barrier" ::: "memory")
; #define AT_LOAD(K_, V_, kt) do { const bf16_t* s_ = kvsrc + (size_t)(kt) * 64 * NQKV; K_ = *(const bf16x8*)s_; V_ = *(const bf16x8*)(s_ + 1024); } while (0)
; #define AT_STORE(K_, V_, buf) do { *(LAS bf16x8*)(lds + AT_KOFF + (buf) * 9216 + srow * 144 + sch * 16) = K_; \
;         _Pragma("unroll") for (int j_ = 0; j_ < 8; ++j_) *(LAS short*)(lds + AT_VOFF + (buf) * 9216 + (8 * sch + j_) * 144 + vp * 2) = V_[j_]; } while (0)
; __device__ __forceinline__ void attn_tile(const LAS unsigned char* Kb, const LAS unsigned char* Vb, const LAS f32x4* bp, const bf16x8 (&qr)[4], f32x16 (&o)[2], float& m, float& l, int r32, int hi) {
;     ...
;     float ls = 0.f; const float nm = -m;
; #pragma unroll
;     for (int r = 0; r < 16; ++r) { p0[r] = __builtin_amdgcn_exp2f(p0[r] * C2 + nm); p1[r] = __builtin_amdgcn_exp2f(p1[r] * C2 + nm); ls += p0[r] + p1[r]; }
;     l += ls;
;     u32x4 pw[4];
; #pragma unroll
;     for (int s = 0; s < 2; ++s) {
;         pw[s] = (u32x4){pk2(p0[8 * s], p0[8 * s + 1]), pk2(p0[8 * s + 2], p0[8 * s + 3]), pk2(p0[8 * s + 4], p0[8 * s + 5]), pk2(p0[8 * s + 6], p0[8 * s + 7])};
;         pw[2 + s] = (u32x4){pk2(p1[8 * s], p1[8 * s + 1]), pk2(p1[8 * s + 2], p1[8 * s + 3]), pk2(p1[8 * s + 4], p1[8 * s + 5]), pk2(p1[8 * s + 6], p1[8 * s + 7])};
;     }
; #pragma unroll
;     for (int dh = 0; dh < 2; ++dh)
; #pragma unroll
;         for (int ks = 0; ks < 4; ++ks) {
;             const bf16x8 vf = *(const LAS bf16x8*)(Vb + (32 * dh + r32) * 144 + (16 * ks + 8 * hi) * 2);
;             o[dh] = __builtin_amdgcn_mfma_f32_32x32x16_bf16(vf, __builtin_bit_cast(bf16x8, pw[ks]), o[dh], 0, 0, 0);
;         }
; }
; __device__ __forceinline__ void attn_prompt_unit(const Params& P, LAS unsigned char* lds, int li, int b, int h, int g4, const int tid) {
;     ...
;         AT_STORE(kB, vB, 1);
;         LDS_BARRIER();
;         if (kt + 3 <= kt_hi) AT_LOAD(kB, vB, kt + 3);
.Latt_keep_a:
	v_fma_f32 v48, v48, s6, -v117
	v_fma_f32 v49, v49, s6, -v117
	v_fma_f32 v50, v50, s6, -v117
	v_fma_f32 v51, v51, s6, -v117
	v_fma_f32 v52, v52, s6, -v117
	v_fma_f32 v53, v53, s6, -v117
	v_fma_f32 v54, v54, s6, -v117
	v_fma_f32 v55, v55, s6, -v117
	v_exp_f32_e32 v48, v48
	v_exp_f32_e32 v49, v49
	v_exp_f32_e32 v50, v50
	v_exp_f32_e32 v51, v51
	v_exp_f32_e32 v52, v52
	v_exp_f32_e32 v53, v53
	v_exp_f32_e32 v54, v54
	v_exp_f32_e32 v55, v55
	v_add_f32_e32 v130, v48, v49
	v_add_f32_e32 v131, v50, v51
	v_add_f32_e32 v130, v130, v52
	v_add_f32_e32 v131, v131, v53
	v_add_f32_e32 v130, v130, v54
	v_add_f32_e32 v131, v131, v55
	v_cvt_pk_bf16_f32 v48, v48, v49
	v_cvt_pk_bf16_f32 v49, v50, v51
	v_cvt_pk_bf16_f32 v50, v52, v53
	v_cvt_pk_bf16_f32 v51, v54, v55
	v_fma_f32 v56, v56, s6, -v117
	v_fma_f32 v57, v57, s6, -v117
	v_fma_f32 v58, v58, s6, -v117
	v_fma_f32 v59, v59, s6, -v117
	v_fma_f32 v60, v60, s6, -v117
	v_fma_f32 v61, v61, s6, -v117
	v_fma_f32 v62, v62, s6, -v117
	v_fma_f32 v63, v63, s6, -v117
	v_exp_f32_e32 v56, v56
	v_exp_f32_e32 v57, v57
	v_exp_f32_e32 v58, v58
	v_exp_f32_e32 v59, v59
	v_exp_f32_e32 v60, v60
	v_exp_f32_e32 v61, v61
	v_exp_f32_e32 v62, v62
	v_exp_f32_e32 v63, v63
	s_waitcnt lgkmcnt(0)
	v_mfma_f32_32x32x16_bf16 v[16:31], v[138:141], v[48:51], v[16:31]
	v_mfma_f32_32x32x16_bf16 v[0:15], v[154:157], v[48:51], v[0:15]
	v_add_f32_e32 v130, v130, v56
	v_add_f32_e32 v131, v131, v57
	v_add_f32_e32 v130, v130, v58
	v_add_f32_e32 v131, v131, v59
	v_add_f32_e32 v130, v130, v60
	v_add_f32_e32 v131, v131, v61
	v_add_f32_e32 v130, v130, v62
	v_add_f32_e32 v131, v131, v63
	v_cvt_pk_bf16_f32 v52, v56, v57
	v_cvt_pk_bf16_f32 v53, v58, v59
	v_cvt_pk_bf16_f32 v54, v60, v61
	v_cvt_pk_bf16_f32 v55, v62, v63
	v_fma_f32 v32, v32, s6, -v117
	v_fma_f32 v33, v33, s6, -v117
	v_fma_f32 v34, v34, s6, -v117
	v_fma_f32 v35, v35, s6, -v117
	v_fma_f32 v36, v36, s6, -v117
	v_fma_f32 v37, v37, s6, -v117
	v_fma_f32 v38, v38, s6, -v117
	v_fma_f32 v39, v39, s6, -v117
	v_exp_f32_e32 v32, v32
	v_exp_f32_e32 v33, v33
	v_exp_f32_e32 v34, v34
	v_exp_f32_e32 v35, v35
	v_exp_f32_e32 v36, v36
	v_exp_f32_e32 v37, v37
	v_exp_f32_e32 v38, v38
	v_exp_f32_e32 v39, v39
	v_mfma_f32_32x32x16_bf16 v[16:31], v[142:145], v[52:55], v[16:31]
	v_mfma_f32_32x32x16_bf16 v[0:15], v[118:121], v[52:55], v[0:15]
	v_add_f32_e32 v130, v130, v32
	v_add_f32_e32 v131, v131, v33
	v_add_f32_e32 v130, v130, v34
	v_add_f32_e32 v131, v131, v35
	v_add_f32_e32 v130, v130, v36
	v_add_f32_e32 v131, v131, v37
	v_add_f32_e32 v130, v130, v38
	v_add_f32_e32 v131, v131, v39
	v_cvt_pk_bf16_f32 v32, v32, v33
	v_cvt_pk_bf16_f32 v33, v34, v35
	v_cvt_pk_bf16_f32 v34, v36, v37
	v_cvt_pk_bf16_f32 v35, v38, v39
	v_fma_f32 v40, v40, s6, -v117
	v_fma_f32 v41, v41, s6, -v117
	v_fma_f32 v42, v42, s6, -v117
	v_fma_f32 v43, v43, s6, -v117
	v_fma_f32 v44, v44, s6, -v117
	v_fma_f32 v45, v45, s6, -v117
	v_fma_f32 v46, v46, s6, -v117
	v_fma_f32 v47, v47, s6, -v117
	v_exp_f32_e32 v40, v40
	v_exp_f32_e32 v41, v41
	v_exp_f32_e32 v42, v42
	v_exp_f32_e32 v43, v43
	v_exp_f32_e32 v44, v44
	v_exp_f32_e32 v45, v45
	v_exp_f32_e32 v46, v46
	v_exp_f32_e32 v47, v47
	v_mfma_f32_32x32x16_bf16 v[16:31], v[146:149], v[32:35], v[16:31]
	v_mfma_f32_32x32x16_bf16 v[0:15], v[122:125], v[32:35], v[0:15]
	v_add_f32_e32 v130, v130, v40
	v_add_f32_e32 v131, v131, v41
	v_add_f32_e32 v130, v130, v42
	v_add_f32_e32 v131, v131, v43
	v_add_f32_e32 v130, v130, v44
	v_add_f32_e32 v131, v131, v45
	v_add_f32_e32 v130, v130, v46
	v_add_f32_e32 v131, v131, v47
	v_cvt_pk_bf16_f32 v36, v40, v41
	v_cvt_pk_bf16_f32 v37, v42, v43
	v_cvt_pk_bf16_f32 v38, v44, v45
	v_cvt_pk_bf16_f32 v39, v46, v47
	v_add_f32_e32 v130, v130, v131
	v_add_f32_e32 v101, v101, v130
	v_mfma_f32_32x32x16_bf16 v[16:31], v[150:153], v[36:39], v[16:31]
	v_mfma_f32_32x32x16_bf16 v[0:15], v[126:129], v[36:39], v[0:15]
.LBB0_77:
	s_waitcnt vmcnt(1)
	ds_write_b128 v114, v[88:91] offset:9216
	s_waitcnt vmcnt(0)
	ds_write_b128 v114, v[92:95] offset:27648
	s_waitcnt lgkmcnt(0)
	s_barrier
	s_cmp_gt_u32 s28, s15
	s_cbranch_scc1 .LBB0_79
	global_load_dwordx4 v[88:91], v[106:107], off offset:-2048
	global_load_dwordx4 v[92:95], v[106:107], off
; #define LAS __attribute__((address_space(3)))
; __device__ __forceinline__ void attn_tile(const LAS unsigned char* Kb, const LAS unsigned char* Vb, const LAS f32x4* bp, const bf16x8 (&qr)[4], f32x16 (&o)[2], float& m, float& l, int r32, int hi) {
;     const float C2 = 0.125f * LOG2E;
;     f32x16 p0, p1;
; #pragma unroll
;     for (int j = 0; j < 4; ++j) { const f32x4 t0 = bp[j * 64], t1 = bp[(4 + j) * 64];
;         p0[4 * j] = t0[0]; p0[4 * j + 1] = t0[1]; p0[4 * j + 2] = t0[2]; p0[4 * j + 3] = t0[3]; p1[4 * j] = t1[0]; p1[4 * j + 1] = t1[1]; p1[4 * j + 2] = t1[2]; p1[4 * j + 3] = t1[3]; }
; #pragma unroll
;     for (int d0 = 0; d0 < 4; ++d0) {
;         const bf16x8 a0 = *(const LAS bf16x8*)(Kb + r32 * 144 + d0 * 32 + hi * 16);
;         const bf16x8 a1 = *(const LAS bf16x8*)(Kb + (32 + r32) * 144 + d0 * 32 + hi * 16);
;         p0 = __builtin_amdgcn_mfma_f32_32x32x16_bf16(a0, qr[d0], p0, 0, 0, 0);
;         p1 = __builtin_amdgcn_mfma_f32_32x32x16_bf16(a1, qr[d0], p1, 0, 0, 0);
;     }
;     float mx = fmaxf(p0[0], p1[0]);
; #pragma unroll
;     for (int r = 1; r < 16; ++r) mx = fmaxf(mx, fmaxf(p0[r], p1[r]));
;     mx = fmaxf(mx, __shfl_xor(mx, 32)) * C2;
;     if (__any(mx > m + 8.0f)) {
;         const float mn = fmaxf(m, mx), scl = __builtin_amdgcn_exp2f(m - mn); m = mn; l *= scl;
; #pragma unroll
;         for (int r = 0; r < 16; ++r) { o[0][r] *= scl; o[1][r] *= scl; }
;     }
;     float ls = 0.f; const float nm = -m;
; #pragma unroll
;     for (int r = 0; r < 16; ++r) { p0[r] = __builtin_amdgcn_exp2f(p0[r] * C2 + nm); p1[r] = __builtin_amdgcn_exp2f(p1[r] * C2 + nm); ls += p0[r] + p1[r]; }
;     l += ls;
;     u32x4 pw[4];
; #pragma unroll
;     for (int s = 0; s < 2; ++s) {
;         pw[s] = (u32x4){pk2(p0[8 * s], p0[8 * s + 1]), pk2(p0[8 * s + 2], p0[8 * s + 3]), pk2(p0[8 * s + 4], p0[8 * s + 5]), pk2(p0[8 * s + 6], p0[8 * s + 7])};
;         pw[2 + s] = (u32x4){pk2(p1[8 * s], p1[8 * s + 1]), pk2(p1[8 * s + 2], p1[8 * s + 3]), pk2(p1[8 * s + 4], p1[8 * s + 5]), pk2(p1[8 * s + 6], p1[8 * s + 7])};
;     }
; #pragma unroll
;     for (int dh = 0; dh < 2; ++dh)
; #pragma unroll
;         for (int ks = 0; ks < 4; ++ks) {
;             const bf16x8 vf = *(const LAS bf16x8*)(Vb + (32 * dh + r32) * 144 + (16 * ks + 8 * hi) * 2);
.LBB0_79:
	s_add_i32 s29, s28, 1
	s_cmp_lt_i32 s29, s25
	s_cselect_b64 s[30:31], -1, 0
	s_cmp_ge_i32 s28, s23
	s_cselect_b64 s[28:29], -1, 0
	s_or_b64 s[28:29], s[28:29], s[30:31]
	s_and_b64 vcc, exec, s[28:29]
	s_cbranch_vccnz .LBB0_83
	s_add_i32 s28, s22, s26
	s_min_i32 s28, s28, 3
	v_lshl_add_u32 v158, s28, 14, v103
	ds_read_b128 v[48:51], v158 offset:36864
	ds_read_b128 v[52:55], v158 offset:37888
	ds_read_b128 v[56:59], v158 offset:38912
	ds_read_b128 v[60:63], v158 offset:39936
	ds_read_b128 v[138:141], v116 offset:9216
	ds_read_b128 v[142:145], v116 offset:13824
	ds_read_b128 v[32:35], v158 offset:40960
	ds_read_b128 v[36:39], v158 offset:41984
	ds_read_b128 v[40:43], v158 offset:43008
	ds_read_b128 v[44:47], v158 offset:44032
	ds_read_b128 v[146:149], v116 offset:9248
	ds_read_b128 v[150:153], v116 offset:13856
	ds_read_b128 v[154:157], v116 offset:9280
	ds_read_b128 v[118:121], v116 offset:13888
	ds_read_b128 v[122:125], v116 offset:9312
	v_lshrrev_b32_e32 v133, 5, v200
	v_bfe_u32 v159, v200, 2, 2
	v_lshl_add_u32 v133, v133, 2, v159
	v_mul_u32_u24_e32 v133, 0x90, v133
	v_bfe_u32 v159, v200, 4, 1
	v_lshl_add_u32 v133, v159, 5, v133
	v_and_b32_e32 v159, 3, v200
	v_lshl_add_u32 v133, v159, 3, v133
	v_xor_b32_e32 v132, 32, v200
	s_waitcnt lgkmcnt(10)
	v_mfma_f32_32x32x16_bf16 v[48:63], v[138:141], v[64:67], v[48:63]
	ds_read_b128 v[126:129], v116 offset:13920
	s_waitcnt lgkmcnt(6)
	v_mfma_f32_32x32x16_bf16 v[32:47], v[142:145], v[64:67], v[32:47]
	v_lshlrev_b32_e32 v132, 2, v132
	s_waitcnt lgkmcnt(5)
	v_mfma_f32_32x32x16_bf16 v[48:63], v[146:149], v[68:71], v[48:63]
	s_waitcnt lgkmcnt(4)
	v_mfma_f32_32x32x16_bf16 v[32:47], v[150:153], v[68:71], v[32:47]
	s_waitcnt lgkmcnt(3)
	v_mfma_f32_32x32x16_bf16 v[48:63], v[154:157], v[72:75], v[48:63]
	s_waitcnt lgkmcnt(2)
	v_mfma_f32_32x32x16_bf16 v[32:47], v[118:121], v[72:75], v[32:47]
	s_waitcnt lgkmcnt(1)
	v_mfma_f32_32x32x16_bf16 v[48:63], v[122:125], v[80:83], v[48:63]
	s_waitcnt lgkmcnt(0)
	v_mfma_f32_32x32x16_bf16 v[32:47], v[126:129], v[80:83], v[32:47]
	ds_read_b64_tr_b16 v[138:139], v133 offset:27648
	ds_read_b64_tr_b16 v[140:141], v133 offset:28800
	ds_read_b64_tr_b16 v[142:143], v133 offset:29952
	ds_read_b64_tr_b16 v[144:145], v133 offset:31104
	ds_read_b64_tr_b16 v[146:147], v133 offset:32256
	ds_read_b64_tr_b16 v[148:149], v133 offset:33408
	ds_read_b64_tr_b16 v[150:151], v133 offset:34560
	ds_read_b64_tr_b16 v[152:153], v133 offset:35712
	v_add_f32_e32 v159, 0x41000000, v117
	s_nop 1
	v_max3_f32 v130, v48, v49, v50
	v_max3_f32 v130, v130, v51, v52
	v_max3_f32 v130, v130, v53, v54
	v_max3_f32 v131, v32, v33, v34
	v_max3_f32 v130, v130, v55, v56
	v_max3_f32 v131, v131, v35, v36
	v_max3_f32 v130, v130, v57, v58
	v_max3_f32 v131, v131, v37, v38
	v_max3_f32 v130, v130, v59, v60
	v_max3_f32 v131, v131, v39, v40
	v_max3_f32 v130, v130, v61, v62
	v_max3_f32 v131, v131, v41, v42
	v_max_f32_e32 v130, v130, v63
	v_max3_f32 v131, v131, v43, v44
	v_max3_f32 v131, v131, v45, v46
	v_max_f32_e32 v131, v131, v47
	v_max_f32_e32 v130, v130, v131
	ds_bpermute_b32 v131, v132, v130
	s_waitcnt lgkmcnt(0)
	v_max_f32_e32 v130, v130, v131
	v_mul_f32_e32 v130, 0x3e38aa3b, v130
	v_cmp_gt_f32_e32 vcc, v130, v159
	ds_read_b64_tr_b16 v[154:155], v133 offset:27712
	ds_read_b64_tr_b16 v[156:157], v133 offset:28864
	ds_read_b64_tr_b16 v[118:119], v133 offset:30016
	ds_read_b64_tr_b16 v[120:121], v133 offset:31168
	ds_read_b64_tr_b16 v[122:123], v133 offset:32320
	ds_read_b64_tr_b16 v[124:125], v133 offset:33472
	ds_read_b64_tr_b16 v[126:127], v133 offset:34624
	ds_read_b64_tr_b16 v[128:129], v133 offset:35776
	s_cbranch_vccz .Latt_keep_b
	v_max_f32_e32 v131, v117, v130
	v_sub_f32_e32 v117, v117, v131
	v_exp_f32_e32 v130, v117
	v_mov_b32_e32 v117, v131
	v_mul_f32_e32 v101, v101, v130
	v_pk_mul_f32 v[0:1], v[0:1], v[130:131] op_sel_hi:[1,0]
	v_pk_mul_f32 v[2:3], v[2:3], v[130:131] op_sel_hi:[1,0]
	v_pk_mul_f32 v[4:5], v[4:5], v[130:131] op_sel_hi:[1,0]
	v_pk_mul_f32 v[6:7], v[6:7], v[130:131] op_sel_hi:[1,0]
	v_pk_mul_f32 v[8:9], v[8:9], v[130:131] op_sel_hi:[1,0]
	v_pk_mul_f32 v[10:11], v[10:11], v[130:131] op_sel_hi:[1,0]
	v_pk_mul_f32 v[12:13], v[12:13], v[130:131] op_sel_hi:[1,0]
	v_pk_mul_f32 v[14:15], v[14:15], v[130:131] op_sel_hi:[1,0]
	v_pk_mul_f32 v[16:17], v[16:17], v[130:131] op_sel_hi:[1,0]
	v_pk_mul_f32 v[18:19], v[18:19], v[130:131] op_sel_hi:[1,0]
	v_pk_mul_f32 v[20:21], v[20:21], v[130:131] op_sel_hi:[1,0]
	v_pk_mul_f32 v[22:23], v[22:23], v[130:131] op_sel_hi:[1,0]
	v_pk_mul_f32 v[24:25], v[24:25], v[130:131] op_sel_hi:[1,0]
	v_pk_mul_f32 v[26:27], v[26:27], v[130:131] op_sel_hi:[1,0]
	v_pk_mul_f32 v[28:29], v[28:29], v[130:131] op_sel_hi:[1,0]
	v_pk_mul_f32 v[30:31], v[30:31], v[130:131] op_sel_hi:[1,0]

; #define AT_STORE(K_, V_, buf) do { *(LAS bf16x8*)(lds + AT_KOFF + (buf) * 9216 + srow * 144 + sch * 16) = K_; \
;         _Pragma("unroll") for (int j_ = 0; j_ < 8; ++j_) *(LAS short*)(lds + AT_VOFF + (buf) * 9216 + (8 * sch + j_) * 144 + vp * 2) = V_[j_]; } while (0)
; __device__ __forceinline__ void attn_prompt_unit(const Params& P, LAS unsigned char* lds, int li, int b, int h, int g4, const int tid) {
;     ...
;         if (kt + 2 <= kt_hi) AT_STORE(kA, vA, 0);
.LBB0_83:
	s_andn2_b64 vcc, exec, s[18:19]
	s_cbranch_vccnz .LBB0_85
	ds_write_b128 v114, v[76:79]
	ds_write_b128 v114, v[84:87] offset:18432
